# incremental next-tile update (pn+=4 with wrap) when grid==256, and removed the compiler's vmcnt(0) drain after the GEMM prologue
# speedup vs baseline: 1.0133x; 1.0023x over previous
; #define PG8_STAGE(bufoff, gbase, voff) do { _Pragma("unroll") for (int _i = 0; _i < 2; ++_i) \
;         __builtin_amdgcn_global_load_lds((const unsigned*)((const char*)(gbase) + (voff)[_i]), (PG8_LAS unsigned*)(lds + (bufoff) + ldsw + _i * 8192), 16, 0, 0); } while (0)
; #define PG8_WAIT_V(n) asm volatile("s_waitcnt vmcnt(" #n ")" ::: "memory")
; #define PG8_BAR __builtin_amdgcn_s_barrier()
; template <class Epi, class Sched, bool ALIGN_EPI = false, bool SP2 = false>
; __device__ __forceinline__ void gemm_phase(PG8_LAS unsigned char* lds, const Gemm g, const Sched& S, const Epi& E) {
;     ...
;         PG8_STAGE(PG8_SB(0, 0), cB, voffB); PG8_STAGE(PG8_SB(0, 1), cB + hstep, voffB); PG8_STAGE(PG8_SA(0, 0), cA, voffA); PG8_STAGE(PG8_SA(0, 1), cA + hstep, voffA);
;         if (wr == 1) PG8_BAR;
;         PG8_WAIT_V(2); PG8_BAR;
;         PG8_STAGE(PG8_SB(1, 0), cB + kstep, voffB); PG8_STAGE(PG8_SA(1, 0), cA + kstep, voffA); PG8_STAGE(PG8_SB(1, 1), cB + hstep + kstep, voffB);
;         PG8_WAIT_V(6); PG8_BAR;
.LBB0_223:
	s_and_b64 s[6:7], s[6:7], exec
	s_cselect_b32 s15, s93, s95
	s_cselect_b32 s14, s92, s94
	s_add_i32 m0, s35, 0x18000
	v_lshl_add_u64 v[2:3], v[2:3], 0, s[86:87]
	s_waitcnt vmcnt(2)
	s_barrier
	global_load_lds_dwordx4 v[2:3], off
	v_lshl_add_u64 v[2:3], v[4:5], 0, s[86:87]
	s_add_i32 m0, s35, 0x1a000
	s_add_i32 s40, s35, 0x8000
	global_load_lds_dwordx4 v[2:3], off
	v_lshl_add_u64 v[2:3], v[10:11], 0, s[86:87]
	s_mov_b32 m0, s40
	s_add_i32 s41, s35, 0xa000
	global_load_lds_dwordx4 v[2:3], off
	v_lshl_add_u64 v[2:3], v[12:13], 0, s[86:87]
	s_mov_b32 m0, s41
	v_lshlrev_b32_e32 v17, 2, v154
	global_load_lds_dwordx4 v[2:3], off
	s_add_i32 m0, s35, 0x1c000
	v_lshl_add_u64 v[2:3], v[6:7], 0, s[86:87]
	global_load_lds_dwordx4 v[2:3], off
	v_lshl_add_u64 v[2:3], v[8:9], 0, s[86:87]
	s_add_i32 m0, s35, 0x1e000
	v_lshl_or_b32 v16, v154, 6, v156
	global_load_lds_dwordx4 v[2:3], off
	s_lshl_b32 s6, s17, 13
	v_and_b32_e32 v17, 32, v17
	s_lshr_b32 s39, s16, 6
	v_bitop3_b32 v16, v16, s6, v17 bitop3:0xde
	s_lshl_b32 s6, s11, 5
	s_and_b32 s6, s6, 0x60
	s_waitcnt vmcnt(6)
	s_add_i32 s43, s39, -2
	v_add_lshl_u32 v2, v163, v15, 1
	v_mov_b32_e32 v3, v1
	s_cmpk_lt_u32 s9, 0x100
	v_lshl_add_u64 v[150:151], s[62:63], 0, v[2:3]
	v_add_lshl_u32 v2, v163, v14, 1
	s_sext_i32_i16 s51, s8
	v_lshl_or_b32 v171, s17, 6, v154
	v_lshl_or_b32 v172, s6, 7, v157
	s_cselect_b64 s[16:17], -1, 0
	s_mov_b32 s11, s63
	v_or_b32_e32 v173, s6, v155
	v_lshl_add_u64 v[152:153], s[62:63], 0, v[2:3]
	s_mov_b32 s48, 0
	v_add_u32_e32 v174, 0, v16
	s_barrier
	s_branch .LBB0_226

;     __host__ __device__ bool next(int i, Unit& u) const {
;         const long L = (long)i * G + c; if (L >= nwg) return false;
;         int wgid = (int)L; { const int q = nwg / NXCD, r = nwg % NXCD, xcd = wgid % NXCD, off = wgid / NXCD; wgid = (xcd < r ? xcd * (q + 1) : r * (q + 1) + (xcd - r) * q) + off; }
;         const int nig = WGM * nN, gid = wgid / nig, fm = gid * WGM, gsz = (nM - fm) < WGM ? (nM - fm) : WGM;
;         u.pm = fm + ((wgid % nig) % gsz); u.pn = (wgid % nig) / gsz; return true;
; template <class Epi, class Sched, bool ALIGN_EPI = false, bool SP2 = false>
; __device__ __forceinline__ void gemm_phase(PG8_LAS unsigned char* lds, const Gemm g, const Sched& S, const Epi& E) {
;     ...
;         const bool has_next = S.next(ui + 1, nxt);
;         const char* nA = has_next ? (const char*)g.A + (size_t)nxt.pm * tstep : cA; const char* nB = has_next ? (const char*)g.Bt + (size_t)nxt.pn * tstep : cB;
.LBB0_226:
	s_add_i32 s48, s48, 1
	s_mul_i32 s6, s48, s53
	s_mul_hi_u32 s7, s48, s52
	s_add_i32 s7, s7, s6
	s_mul_i32 s6, s48, s52
	s_add_u32 s6, s6, s2
	s_addc_u32 s7, s7, s3
	v_mov_b64_e32 v[2:3], s[10:11]
	v_cmp_ge_i64_e32 vcc, s[6:7], v[2:3]
	v_cmp_lt_i64_e64 s[8:9], s[6:7], v[2:3]
	s_cbranch_vccnz .LBB0_228
	s_cmpk_lg_u32 s52, 0x100
	s_cbranch_scc1 .LA_next_slow
	s_lshr_b32 vcc_lo, s1, 8
	s_add_i32 s49, s51, 4
	s_mov_b32 s50, s42
	s_cmp_lt_i32 s49, vcc_lo
	s_cbranch_scc1 .LBB0_228
	s_sub_i32 s49, s49, vcc_lo
	s_add_i32 s50, s50, 8
	s_branch .LBB0_228
.LA_next_slow:
	s_ashr_i32 s7, s6, 31
	s_lshr_b32 s7, s7, 29
	s_add_i32 s7, s6, s7
	s_ashr_i32 s18, s7, 3
	s_and_b32 s7, s7, -8
	s_sub_i32 s6, s6, s7
	s_cmp_lt_i32 s6, 0
	s_cselect_b32 s7, s31, s30
	s_mul_i32 s6, s7, s6
	s_add_i32 s6, s6, s18
	s_abs_i32 s18, s6
	s_mul_hi_u32 s19, s18, s34
	s_mul_i32 s49, s19, s29
	s_sub_i32 s18, s18, s49
	s_ashr_i32 s7, s6, 31
	s_add_i32 s49, s19, 1
	s_sub_i32 s50, s18, s29
	s_cmp_ge_u32 s18, s29
	s_cselect_b32 s19, s49, s19
	s_cselect_b32 s18, s50, s18
	s_add_i32 s49, s19, 1
	s_cmp_ge_u32 s18, s29
	s_cselect_b32 s18, s49, s19
	s_xor_b32 s18, s18, s7
	s_sub_i32 s7, s18, s7
	s_lshl_b32 s18, s7, 3
	s_sub_i32 s19, 0x80, s18
	s_min_i32 s19, s19, 8
	s_abs_i32 s49, s19
	v_cvt_f32_u32_e32 v2, s49
	s_sub_i32 s54, 0, s49
	s_mul_i32 s7, s7, s29
	s_sub_i32 s6, s6, s7
	v_rcp_iflag_f32_e32 v2, v2
	s_abs_i32 s50, s6
	s_xor_b32 s7, s6, s19
	s_ashr_i32 s7, s7, 31
	v_mul_f32_e32 v2, 0x4f7ffffe, v2
	v_cvt_u32_f32_e32 v2, v2
	s_nop 0
	v_readfirstlane_b32 s55, v2
	s_mul_i32 s54, s54, s55
	s_mul_hi_u32 s54, s55, s54
	s_add_i32 s55, s55, s54
	s_mul_hi_u32 s54, s50, s55
	s_mul_i32 s55, s54, s49
	s_sub_i32 s50, s50, s55
	s_add_i32 s55, s54, 1
	s_sub_i32 s56, s50, s49
	s_cmp_ge_u32 s50, s49
	s_cselect_b32 s54, s55, s54
	s_cselect_b32 s50, s56, s50
	s_add_i32 s55, s54, 1
	s_cmp_ge_u32 s50, s49
	s_cselect_b32 s49, s55, s54
	s_xor_b32 s49, s49, s7
	s_sub_i32 s49, s49, s7
	s_mul_i32 s7, s49, s19
	s_sub_i32 s6, s6, s7
	s_add_i32 s50, s6, s18

;     __host__ __device__ bool next(int i, Unit& u) const {
;         const long L = (long)i * G + c; if (L >= nwg) return false;
;         int wgid = (int)L; { const int q = nwg / NXCD, r = nwg % NXCD, xcd = wgid % NXCD, off = wgid / NXCD; wgid = (xcd < r ? xcd * (q + 1) : r * (q + 1) + (xcd - r) * q) + off; }
;         const int nig = WGM * nN, gid = wgid / nig, fm = gid * WGM, gsz = (nM - fm) < WGM ? (nM - fm) : WGM;
;         u.pm = fm + ((wgid % nig) % gsz); u.pn = (wgid % nig) / gsz; return true;
; template <class Epi, class Sched, bool ALIGN_EPI = false, bool SP2 = false>
; __device__ __forceinline__ void gemm_phase(PG8_LAS unsigned char* lds, const Gemm g, const Sched& S, const Epi& E) {
;     ...
;         const bool has_next = S.next(ui + 1, nxt);
;         const char* nA = has_next ? (const char*)g.A + (size_t)nxt.pm * tstep : cA; const char* nB = has_next ? (const char*)g.Bt + (size_t)nxt.pn * tstep : cB;
.LBB0_281:
	s_add_i32 s35, s35, 1
	s_mul_i32 s6, s35, s53
	s_mul_hi_u32 s7, s35, s52
	s_add_i32 s7, s7, s6
	s_mul_i32 s6, s35, s52
	s_add_u32 s16, s6, s2
	s_addc_u32 s17, s7, s3
	v_mov_b64_e32 v[2:3], 0xb00
	v_cmp_lt_i64_e64 s[6:7], s[16:17], v[2:3]
	v_mov_b64_e32 v[2:3], 0xaff
	v_cmp_gt_i64_e32 vcc, s[16:17], v[2:3]
	s_cbranch_vccnz .LBB0_283
	s_cmpk_lg_u32 s52, 0x100
	s_cbranch_scc1 .LB_next_slow
	s_add_i32 s12, s36, 4
	s_mov_b32 s14, s37
	s_cmpk_lt_i32 s12, 22
	s_cbranch_scc1 .LBB0_283
	s_addk_i32 s12, 0xffea
	s_add_i32 s14, s14, 8
	s_branch .LBB0_283
.LB_next_slow:
	s_ashr_i32 s12, s16, 31
	s_lshr_b32 s12, s12, 29
	s_add_i32 s12, s16, s12
	s_ashr_i32 s13, s12, 3
	s_and_b32 s12, s12, -8
	s_sub_i32 s12, s16, s12
	s_cmp_lt_i32 s12, 0
	s_cselect_b32 s14, s47, 0x160
	s_mul_i32 s12, s14, s12
	s_add_i32 s12, s12, s13
	s_mul_hi_i32 s13, s12, 0x2e8ba2e9
	s_lshr_b32 s14, s13, 31
	s_ashr_i32 s13, s13, 5
	s_add_i32 s13, s13, s14
	s_lshl_b32 s14, s13, 3
	s_sub_i32 s15, 0x80, s14
	s_min_i32 s15, s15, 8
	s_abs_i32 s16, s15
	v_cvt_f32_u32_e32 v2, s16
	s_sub_i32 s18, 0, s16
	s_mulk_i32 s13, 0xb0
	s_sub_i32 s13, s12, s13
	v_rcp_iflag_f32_e32 v2, v2
	s_abs_i32 s12, s13
	s_xor_b32 s17, s13, s15
	s_ashr_i32 s17, s17, 31
	v_mul_f32_e32 v2, 0x4f7ffffe, v2
	v_cvt_u32_f32_e32 v2, v2
	s_nop 0
	v_readfirstlane_b32 s19, v2
	s_mul_i32 s18, s18, s19
	s_mul_hi_u32 s18, s19, s18
	s_add_i32 s19, s19, s18
	s_mul_hi_u32 s18, s12, s19
	s_mul_i32 s19, s18, s16
	s_sub_i32 s12, s12, s19
	s_add_i32 s24, s18, 1
	s_sub_i32 s19, s12, s16
	s_cmp_ge_u32 s12, s16
	s_cselect_b32 s18, s24, s18
	s_cselect_b32 s12, s19, s12
	s_add_i32 s19, s18, 1
	s_cmp_ge_u32 s12, s16
	s_cselect_b32 s12, s19, s18
	s_xor_b32 s12, s12, s17
	s_sub_i32 s12, s12, s17
	s_mul_i32 s15, s12, s15
	s_sub_i32 s13, s13, s15
	s_add_i32 s14, s13, s14
